# v35 + grid-barrier release flattened (all workgroups wait on the cross-XCC generation word, XCC release add dropped) + P8/P16 fix-up single wait per item + band-attention LDS fragment reads batched
# speedup vs baseline: 1.0063x; 1.0025x over previous
.LBB0_162:
	s_lshl_b32 s6, s75, 8
	s_add_u32 s6, s88, s6
	s_addc_u32 s7, s89, 0
	v_mov_b32_e32 v1, 0x1000
	v_mov_b32_e32 v3, 1
	global_atomic_add v3, v1, v3, s[6:7] offset:1024 sc0
	v_cvt_f32_u32_e32 v1, v2
	v_sub_u32_e32 v4, 0, v2
	v_rcp_iflag_f32_e32 v1, v1
	s_nop 0
	v_mul_f32_e32 v1, 0x4f7ffffe, v1
	v_cvt_u32_f32_e32 v1, v1
	v_mul_lo_u32 v4, v4, v1
	v_mul_hi_u32 v4, v1, v4
	v_add_u32_e32 v1, v1, v4
	s_waitcnt vmcnt(0)
	v_mul_hi_u32 v1, v3, v1
	v_mul_lo_u32 v4, v1, v2
	v_sub_u32_e32 v4, v3, v4
	v_add_u32_e32 v5, 1, v1
	v_cmp_ge_u32_e32 vcc, v4, v2
	v_add_u32_e32 v3, 1, v3
	s_nop 0
	v_cndmask_b32_e32 v1, v1, v5, vcc
	v_sub_u32_e32 v5, v4, v2
	v_cndmask_b32_e32 v4, v4, v5, vcc
	v_add_u32_e32 v5, 1, v1
	v_cmp_ge_u32_e32 vcc, v4, v2
	s_nop 1
	v_cndmask_b32_e32 v1, v1, v5, vcc
	v_mul_lo_u32 v4, v2, v1
	v_add_u32_e32 v2, v4, v2
	v_cmp_ne_u32_e32 vcc, v3, v2
	s_and_saveexec_b64 s[8:9], vcc
	s_xor_b64 s[8:9], exec, s[8:9]
	s_cbranch_execz .LBB0_176
	s_waitcnt lgkmcnt(0)
	v_mov_b32_e32 v0, 0x3100
	global_load_dword v0, v0, s[88:89] offset:1024 sc1
	s_add_u32 s14, s88, 0x3500
	s_addc_u32 s15, s89, 0
	s_waitcnt vmcnt(0)
	v_cmp_eq_u32_e32 vcc, v0, v1
	s_and_saveexec_b64 s[10:11], vcc
	s_cbranch_execz .LBB0_175
	s_mov_b32 s28, 1
	s_mov_b64 s[16:17], 0
	v_mov_b32_e32 v0, 0
	s_branch .LBB0_166

.LBB0_193:
	s_or_b64 exec, exec, s[8:9]
	v_mov_b32_e32 v0, 0x2000
	v_mov_b32_e32 v1, 1
	s_waitcnt vmcnt(0)
	buffer_inv sc1
	s_waitcnt vmcnt(0)

.LBB0_249:
	s_lshl_b32 s4, s75, 8
	s_add_u32 s4, s88, s4
	s_addc_u32 s5, s89, 0
	v_mov_b32_e32 v1, 0x1000
	v_mov_b32_e32 v3, 1
	global_atomic_add v3, v1, v3, s[4:5] offset:1024 sc0
	v_cvt_f32_u32_e32 v1, v2
	v_sub_u32_e32 v4, 0, v2
	v_rcp_iflag_f32_e32 v1, v1
	s_nop 0
	v_mul_f32_e32 v1, 0x4f7ffffe, v1
	v_cvt_u32_f32_e32 v1, v1
	v_mul_lo_u32 v4, v4, v1
	v_mul_hi_u32 v4, v1, v4
	v_add_u32_e32 v1, v1, v4
	s_waitcnt vmcnt(0)
	v_mul_hi_u32 v1, v3, v1
	v_mul_lo_u32 v4, v1, v2
	v_sub_u32_e32 v4, v3, v4
	v_add_u32_e32 v5, 1, v1
	v_cmp_ge_u32_e32 vcc, v4, v2
	v_add_u32_e32 v3, 1, v3
	s_nop 0
	v_cndmask_b32_e32 v1, v1, v5, vcc
	v_sub_u32_e32 v5, v4, v2
	v_cndmask_b32_e32 v4, v4, v5, vcc
	v_add_u32_e32 v5, 1, v1
	v_cmp_ge_u32_e32 vcc, v4, v2
	s_nop 1
	v_cndmask_b32_e32 v1, v1, v5, vcc
	v_mul_lo_u32 v4, v2, v1
	v_add_u32_e32 v2, v4, v2
	v_cmp_ne_u32_e32 vcc, v3, v2
	s_and_saveexec_b64 s[6:7], vcc
	s_xor_b64 s[6:7], exec, s[6:7]
	s_cbranch_execz .LBB0_263
	s_waitcnt lgkmcnt(0)
	v_mov_b32_e32 v0, 0x3100
	global_load_dword v0, v0, s[88:89] offset:1024 sc1
	s_add_u32 s10, s88, 0x3500
	s_addc_u32 s11, s89, 0
	s_waitcnt vmcnt(0)
	v_cmp_eq_u32_e32 vcc, v0, v1
	s_and_saveexec_b64 s[8:9], vcc
	s_cbranch_execz .LBB0_262
	s_mov_b32 s25, 1
	s_mov_b64 s[12:13], 0
	v_mov_b32_e32 v0, 0
	s_branch .LBB0_253

.LBB0_280:
	s_or_b64 exec, exec, s[6:7]
	v_mov_b32_e32 v0, 0x2000
	v_mov_b32_e32 v1, 1
	s_waitcnt vmcnt(0)
	buffer_inv sc1
	s_waitcnt vmcnt(0)

.LBB0_341:
	s_lshl_b32 s6, s75, 8
	s_add_u32 s6, s88, s6
	s_addc_u32 s7, s89, 0
	v_mov_b32_e32 v1, 0x1000
	v_mov_b32_e32 v3, 1
	global_atomic_add v3, v1, v3, s[6:7] offset:1024 sc0
	v_cvt_f32_u32_e32 v1, v2
	v_sub_u32_e32 v4, 0, v2
	v_rcp_iflag_f32_e32 v1, v1
	s_nop 0
	v_mul_f32_e32 v1, 0x4f7ffffe, v1
	v_cvt_u32_f32_e32 v1, v1
	v_mul_lo_u32 v4, v4, v1
	v_mul_hi_u32 v4, v1, v4
	v_add_u32_e32 v1, v1, v4
	s_waitcnt vmcnt(0)
	v_mul_hi_u32 v1, v3, v1
	v_mul_lo_u32 v4, v1, v2
	v_sub_u32_e32 v4, v3, v4
	v_add_u32_e32 v5, 1, v1
	v_cmp_ge_u32_e32 vcc, v4, v2
	v_add_u32_e32 v3, 1, v3
	s_nop 0
	v_cndmask_b32_e32 v1, v1, v5, vcc
	v_sub_u32_e32 v5, v4, v2
	v_cndmask_b32_e32 v4, v4, v5, vcc
	v_add_u32_e32 v5, 1, v1
	v_cmp_ge_u32_e32 vcc, v4, v2
	s_nop 1
	v_cndmask_b32_e32 v1, v1, v5, vcc
	v_mul_lo_u32 v4, v2, v1
	v_add_u32_e32 v2, v4, v2
	v_cmp_ne_u32_e32 vcc, v3, v2
	s_and_saveexec_b64 s[8:9], vcc
	s_xor_b64 s[8:9], exec, s[8:9]
	s_cbranch_execz .LBB0_355
	s_waitcnt lgkmcnt(0)
	v_mov_b32_e32 v0, 0x3100
	global_load_dword v0, v0, s[88:89] offset:1024 sc1
	s_add_u32 s12, s88, 0x3500
	s_addc_u32 s13, s89, 0
	s_waitcnt vmcnt(0)
	v_cmp_eq_u32_e32 vcc, v0, v1
	s_and_saveexec_b64 s[10:11], vcc
	s_cbranch_execz .LBB0_354
	s_mov_b32 s30, 1
	s_mov_b64 s[14:15], 0
	v_mov_b32_e32 v0, 0
	s_branch .LBB0_345

.LBB0_579:
	s_lshl_b32 s4, s75, 8
	s_add_u32 s4, s88, s4
	s_addc_u32 s5, s89, 0
	v_mov_b32_e32 v1, 0x1000
	v_mov_b32_e32 v3, 1
	global_atomic_add v3, v1, v3, s[4:5] offset:1024 sc0
	v_cvt_f32_u32_e32 v1, v2
	v_sub_u32_e32 v4, 0, v2
	v_rcp_iflag_f32_e32 v1, v1
	s_nop 0
	v_mul_f32_e32 v1, 0x4f7ffffe, v1
	v_cvt_u32_f32_e32 v1, v1
	v_mul_lo_u32 v4, v4, v1
	v_mul_hi_u32 v4, v1, v4
	v_add_u32_e32 v1, v1, v4
	s_waitcnt vmcnt(0)
	v_mul_hi_u32 v1, v3, v1
	v_mul_lo_u32 v4, v1, v2
	v_sub_u32_e32 v4, v3, v4
	v_add_u32_e32 v5, 1, v1
	v_cmp_ge_u32_e32 vcc, v4, v2
	v_add_u32_e32 v3, 1, v3
	s_nop 0
	v_cndmask_b32_e32 v1, v1, v5, vcc
	v_sub_u32_e32 v5, v4, v2
	v_cndmask_b32_e32 v4, v4, v5, vcc
	v_add_u32_e32 v5, 1, v1
	v_cmp_ge_u32_e32 vcc, v4, v2
	s_nop 1
	v_cndmask_b32_e32 v1, v1, v5, vcc
	v_mul_lo_u32 v4, v2, v1
	v_add_u32_e32 v2, v4, v2
	v_cmp_ne_u32_e32 vcc, v3, v2
	s_and_saveexec_b64 s[6:7], vcc
	s_xor_b64 s[6:7], exec, s[6:7]
	s_cbranch_execz .LBB0_593
	s_waitcnt lgkmcnt(0)
	v_mov_b32_e32 v0, 0x3100
	global_load_dword v0, v0, s[88:89] offset:1024 sc1
	s_add_u32 s10, s88, 0x3500
	s_addc_u32 s11, s89, 0
	s_waitcnt vmcnt(0)
	v_cmp_eq_u32_e32 vcc, v0, v1
	s_and_saveexec_b64 s[8:9], vcc
	s_cbranch_execz .LBB0_592
	s_mov_b32 s24, 1
	s_mov_b64 s[12:13], 0
	v_mov_b32_e32 v0, 0
	s_branch .LBB0_583

.LBB0_670:
	s_lshl_b32 s2, s75, 8
	s_add_u32 s2, s88, s2
	s_addc_u32 s3, s89, 0
	v_mov_b32_e32 v1, 0x1000
	v_mov_b32_e32 v3, 1
	global_atomic_add v3, v1, v3, s[2:3] offset:1024 sc0
	v_cvt_f32_u32_e32 v1, v2
	v_sub_u32_e32 v4, 0, v2
	v_rcp_iflag_f32_e32 v1, v1
	s_nop 0
	v_mul_f32_e32 v1, 0x4f7ffffe, v1
	v_cvt_u32_f32_e32 v1, v1
	v_mul_lo_u32 v4, v4, v1
	v_mul_hi_u32 v4, v1, v4
	v_add_u32_e32 v1, v1, v4
	s_waitcnt vmcnt(0)
	v_mul_hi_u32 v1, v3, v1
	v_mul_lo_u32 v4, v1, v2
	v_sub_u32_e32 v4, v3, v4
	v_add_u32_e32 v5, 1, v1
	v_cmp_ge_u32_e32 vcc, v4, v2
	v_add_u32_e32 v3, 1, v3
	s_nop 0
	v_cndmask_b32_e32 v1, v1, v5, vcc
	v_sub_u32_e32 v5, v4, v2
	v_cndmask_b32_e32 v4, v4, v5, vcc
	v_add_u32_e32 v5, 1, v1
	v_cmp_ge_u32_e32 vcc, v4, v2
	s_nop 1
	v_cndmask_b32_e32 v1, v1, v5, vcc
	v_mul_lo_u32 v4, v2, v1
	v_add_u32_e32 v2, v4, v2
	v_cmp_ne_u32_e32 vcc, v3, v2
	s_and_saveexec_b64 s[4:5], vcc
	s_xor_b64 s[4:5], exec, s[4:5]
	s_cbranch_execz .LBB0_684
	s_waitcnt lgkmcnt(0)
	v_mov_b32_e32 v0, 0x3100
	global_load_dword v0, v0, s[88:89] offset:1024 sc1
	s_add_u32 s8, s88, 0x3500
	s_addc_u32 s9, s89, 0
	s_waitcnt vmcnt(0)
	v_cmp_eq_u32_e32 vcc, v0, v1
	s_and_saveexec_b64 s[6:7], vcc
	s_cbranch_execz .LBB0_683
	s_mov_b32 s20, 1
	s_mov_b64 s[10:11], 0
	v_mov_b32_e32 v0, 0
	s_branch .LBB0_674

.LBB0_701:
	s_or_b64 exec, exec, s[4:5]
	v_mov_b32_e32 v0, 0x2000
	v_mov_b32_e32 v1, 1
	s_waitcnt vmcnt(0)
	buffer_inv sc1
	s_waitcnt vmcnt(0)

.LBB0_704:
	s_or_b64 exec, exec, s[4:5]
	s_waitcnt vmcnt(0)
	buffer_inv sc1
	s_waitcnt vmcnt(0)

.LBB0_764:
	v_readlane_b32 s6, v249, 7
	v_readlane_b32 s7, v249, 8
	v_cvt_f32_u32_e32 v1, v2
	v_sub_u32_e32 v4, 0, v2
	v_rcp_iflag_f32_e32 v1, v1
	s_nop 1
	global_atomic_add v3, v153, v190, s[6:7] sc0
	v_mul_f32_e32 v1, 0x4f7ffffe, v1
	v_cvt_u32_f32_e32 v1, v1
	v_mul_lo_u32 v4, v4, v1
	v_mul_hi_u32 v4, v1, v4
	v_add_u32_e32 v1, v1, v4
	s_waitcnt vmcnt(0)
	v_mul_hi_u32 v1, v3, v1
	v_mul_lo_u32 v4, v1, v2
	v_sub_u32_e32 v4, v3, v4
	v_add_u32_e32 v5, 1, v1
	v_cmp_ge_u32_e32 vcc, v4, v2
	v_add_u32_e32 v3, 1, v3
	s_nop 0
	v_cndmask_b32_e32 v1, v1, v5, vcc
	v_sub_u32_e32 v5, v4, v2
	v_cndmask_b32_e32 v4, v4, v5, vcc
	v_add_u32_e32 v5, 1, v1
	v_cmp_ge_u32_e32 vcc, v4, v2
	s_nop 1
	v_cndmask_b32_e32 v1, v1, v5, vcc
	v_mul_lo_u32 v4, v2, v1
	v_add_u32_e32 v2, v4, v2
	v_cmp_ne_u32_e32 vcc, v3, v2
	s_and_saveexec_b64 s[6:7], vcc
	s_xor_b64 s[6:7], exec, s[6:7]
	s_cbranch_execz .LBB0_778
	s_waitcnt lgkmcnt(0)
	v_mov_b32_e32 v0, 0x3100
	global_load_dword v0, v0, s[88:89] offset:1024 sc1
	s_waitcnt vmcnt(0)
	v_cmp_eq_u32_e32 vcc, v0, v1
	s_and_saveexec_b64 s[8:9], vcc
	s_cbranch_execz .LBB0_777
	s_mov_b32 s3, 1
	s_mov_b64 s[12:13], 0
	s_branch .LBB0_768

.LBB0_770:
	v_mov_b32_e32 v0, 0x3100
	global_load_dword v0, v0, s[88:89] offset:1024 sc1
	s_add_i32 s3, s3, 1
	s_mov_b64 s[28:29], -1
	s_waitcnt vmcnt(0)
	v_cmp_ne_u32_e32 vcc, v0, v1
	s_orn2_b64 s[26:27], vcc, exec
	s_branch .LBB0_767

.LBB0_793:
	s_or_b64 exec, exec, s[6:7]
	s_and_saveexec_b64 s[6:7], s[8:9]
	s_cbranch_execz .LBB0_795
	global_atomic_add v[0:1], v190, off
.LBB0_795:
	s_or_b64 exec, exec, s[6:7]
	s_waitcnt vmcnt(0)
	buffer_inv sc1
	s_waitcnt vmcnt(0)
.LBB0_796:
	s_or_b64 exec, exec, s[4:5]
	s_waitcnt lgkmcnt(0)
	s_barrier

.LBB0_800:
	s_or_b64 exec, exec, s[26:27]
	s_movk_i32 s11, 0x2000
	v_add_co_u32_e32 v0, vcc, s11, v4
	s_movk_i32 s3, 0x4000
	s_nop 0
	v_addc_co_u32_e32 v1, vcc, 0, v5, vcc
	global_load_dwordx4 v[12:15], v[0:1], off offset:3072
	v_add_co_u32_e32 v0, vcc, s3, v4
	s_movk_i32 s14, 0x5000
	s_nop 0
	v_addc_co_u32_e32 v1, vcc, 0, v5, vcc
	v_add_co_u32_e32 v6, vcc, s14, v4
	s_movk_i32 s3, 0x6000
	s_nop 0
	v_addc_co_u32_e32 v7, vcc, 0, v5, vcc
	v_add_co_u32_e32 v4, vcc, s3, v4
	global_load_dwordx4 v[0:3], v[0:1], off offset:512
	s_nop 0
	v_addc_co_u32_e32 v5, vcc, 0, v5, vcc
	global_load_dwordx4 v[8:11], v[4:5], off offset:3584
	v_lshlrev_b64 v[4:5], 2, v[48:49]
	v_lshl_add_u64 v[24:25], s[8:9], 0, v[4:5]
	s_mov_b64 s[22:23], 0x2c00
	v_add_co_u32_e32 v22, vcc, s11, v24
	v_lshl_add_u64 v[20:21], v[24:25], 0, s[22:23]
	s_mov_b64 s[22:23], 0x5800
	v_addc_co_u32_e32 v23, vcc, 0, v25, vcc
	global_load_dwordx4 v[16:19], v[6:7], off offset:2048
	v_lshl_add_u64 v[26:27], v[24:25], 0, s[22:23]
	v_lshl_add_u64 v[44:45], s[12:13], 0, v[4:5]
	global_load_dwordx4 v[4:7], v[24:25], off offset:16
	global_load_dwordx4 v[32:35], v[24:25], off
	global_load_dwordx4 v[40:43], v[22:23], off offset:3072
	s_nop 0
	global_load_dwordx4 v[20:23], v[20:21], off offset:16
	v_add_co_u32_e32 v24, vcc, s14, v24
	s_movk_i32 s3, 0x1600
	s_nop 0
	v_addc_co_u32_e32 v25, vcc, 0, v25, vcc
	global_load_dwordx4 v[36:39], v[24:25], off offset:2048
	s_nop 0
	global_load_dwordx4 v[24:27], v[26:27], off offset:16
	s_nop 0
	global_load_dwordx4 v[28:31], v[44:45], off offset:16
	s_nop 0
	global_load_dwordx4 v[44:47], v[44:45], off
	v_add_u32_e32 v66, s85, v66
	v_add_u32_e32 v67, s2, v67
	s_waitcnt vmcnt(0)
	s_and_saveexec_b64 s[26:27], s[100:101]
	v_lshlrev_b32_e32 v56, 16, v206
	v_and_b32_e32 v57, 0xffff0000, v206
	v_lshlrev_b32_e32 v62, 16, v207
	v_and_b32_e32 v63, 0xffff0000, v207
	v_lshlrev_b32_e32 v58, 16, v208
	v_and_b32_e32 v59, 0xffff0000, v208
	v_lshlrev_b32_e32 v52, 16, v209
	v_and_b32_e32 v53, 0xffff0000, v209
	v_lshlrev_b32_e32 v64, 16, v210
	v_and_b32_e32 v65, 0xffff0000, v210
	v_lshlrev_b32_e32 v60, 16, v211
	v_and_b32_e32 v61, 0xffff0000, v211
	v_lshlrev_b32_e32 v54, 16, v212
	v_and_b32_e32 v55, 0xffff0000, v212
	v_lshlrev_b32_e32 v50, 16, v213
	v_and_b32_e32 v51, 0xffff0000, v213
	s_or_b64 exec, exec, s[26:27]
	v_lshlrev_b32_e32 v70, 16, v12
	v_and_b32_e32 v71, 0xffff0000, v12
	v_lshlrev_b32_e32 v72, 16, v16
	v_and_b32_e32 v73, 0xffff0000, v16
	v_pk_mul_f32 v[74:75], v[64:65], v[40:41]
	s_nop 0
	v_pk_fma_f32 v[56:57], v[56:57], v[32:33], v[74:75]
	v_pk_mul_f32 v[40:41], v[40:41], v[70:71]
	v_pk_fma_f32 v[56:57], v[36:37], v[70:71], v[56:57]
	v_pk_fma_f32 v[32:33], v[64:65], v[32:33], v[40:41]
	v_pk_add_f32 v[56:57], v[44:45], v[56:57]
	s_nop 0
	v_mul_f32_e32 v12, 0xbfb8aa3b, v56
	v_exp_f32_e32 v12, v12
	s_nop 0
	v_add_f32_e32 v12, 1.0, v12
	v_rcp_f32_e32 v74, v12
	v_mul_f32_e32 v12, 0xbfb8aa3b, v57
	v_exp_f32_e32 v12, v12
	s_nop 0
	v_add_f32_e32 v12, 1.0, v12
	v_rcp_f32_e32 v75, v12
	v_lshlrev_b32_e32 v12, 16, v17
	v_pk_mul_f32 v[56:57], v[56:57], v[74:75]
	s_nop 0
	v_pk_mul_f32 v[56:57], v[56:57], v[72:73]
	v_lshlrev_b32_e32 v72, 16, v0
	v_and_b32_e32 v73, 0xffff0000, v0
	v_pk_fma_f32 v[32:33], v[36:37], v[72:73], v[32:33]
	v_lshlrev_b32_e32 v74, 16, v8
	v_pk_add_f32 v[32:33], v[44:45], v[32:33]
	v_and_b32_e32 v75, 0xffff0000, v8
	v_mul_f32_e32 v0, 0xbfb8aa3b, v32
	v_exp_f32_e32 v0, v0
	v_lshlrev_b32_e32 v8, 16, v9
	v_and_b32_e32 v9, 0xffff0000, v9
	v_add_f32_e32 v0, 1.0, v0
	v_rcp_f32_e32 v36, v0
	v_mul_f32_e32 v0, 0xbfb8aa3b, v33
	v_exp_f32_e32 v0, v0
	s_nop 0
	v_add_f32_e32 v0, 1.0, v0
	v_rcp_f32_e32 v37, v0
	s_nop 0
	v_pk_mul_f32 v[32:33], v[32:33], v[36:37]
	v_lshlrev_b32_e32 v36, 16, v13
	v_and_b32_e32 v37, 0xffff0000, v13
	v_and_b32_e32 v13, 0xffff0000, v17
	v_pk_mul_f32 v[16:17], v[60:61], v[42:43]
	v_pk_mul_f32 v[32:33], v[32:33], v[74:75]
	v_pk_fma_f32 v[16:17], v[62:63], v[34:35], v[16:17]
	s_nop 0
	v_pk_fma_f32 v[16:17], v[38:39], v[36:37], v[16:17]
	s_nop 0
	v_pk_add_f32 v[16:17], v[46:47], v[16:17]
	s_nop 0
	v_mul_f32_e32 v0, 0xbfb8aa3b, v16
	v_exp_f32_e32 v0, v0
	s_nop 0
	v_add_f32_e32 v0, 1.0, v0
	v_rcp_f32_e32 v40, v0
	v_mul_f32_e32 v0, 0xbfb8aa3b, v17
	v_exp_f32_e32 v0, v0
	s_nop 0
	v_add_f32_e32 v0, 1.0, v0
	v_rcp_f32_e32 v41, v0
	v_lshlrev_b32_e32 v0, 16, v1
	v_and_b32_e32 v1, 0xffff0000, v1
	v_pk_mul_f32 v[16:17], v[16:17], v[40:41]
	s_nop 0
	v_pk_mul_f32 v[12:13], v[16:17], v[12:13]
	v_pk_mul_f32 v[16:17], v[42:43], v[36:37]
	s_nop 0
	v_pk_fma_f32 v[16:17], v[60:61], v[34:35], v[16:17]
	v_pk_mul_f32 v[34:35], v[54:55], v[20:21]
	v_pk_fma_f32 v[0:1], v[38:39], v[0:1], v[16:17]
	v_pk_fma_f32 v[34:35], v[58:59], v[4:5], v[34:35]
	v_pk_add_f32 v[0:1], v[46:47], v[0:1]
	s_nop 0
	v_mul_f32_e32 v16, 0xbfb8aa3b, v0
	v_mul_f32_e32 v17, 0xbfb8aa3b, v1
	v_exp_f32_e32 v16, v16
	v_exp_f32_e32 v17, v17
	v_add_f32_e32 v16, 1.0, v16
	v_add_f32_e32 v17, 1.0, v17
	v_rcp_f32_e32 v16, v16
	v_rcp_f32_e32 v17, v17
	s_nop 0
	v_pk_mul_f32 v[0:1], v[0:1], v[16:17]
	s_nop 0
	v_pk_mul_f32 v[0:1], v[0:1], v[8:9]
	v_lshlrev_b32_e32 v8, 16, v14
	v_and_b32_e32 v9, 0xffff0000, v14
	v_pk_fma_f32 v[34:35], v[24:25], v[8:9], v[34:35]
	v_lshlrev_b32_e32 v16, 16, v18
	v_pk_add_f32 v[34:35], v[28:29], v[34:35]
	v_and_b32_e32 v17, 0xffff0000, v18
	v_mul_f32_e32 v14, 0xbfb8aa3b, v34
	v_exp_f32_e32 v14, v14
	v_pk_mul_f32 v[8:9], v[20:21], v[8:9]
	v_add_f32_e32 v14, 1.0, v14
	v_rcp_f32_e32 v36, v14
	v_mul_f32_e32 v14, 0xbfb8aa3b, v35
	v_exp_f32_e32 v14, v14
	v_pk_fma_f32 v[4:5], v[54:55], v[4:5], v[8:9]
	v_add_f32_e32 v14, 1.0, v14
	v_rcp_f32_e32 v37, v14
	v_lshlrev_b32_e32 v14, 16, v19
	v_pk_mul_f32 v[34:35], v[34:35], v[36:37]
	s_nop 0
	v_pk_mul_f32 v[16:17], v[34:35], v[16:17]
	v_lshlrev_b32_e32 v34, 16, v2
	v_and_b32_e32 v35, 0xffff0000, v2
	v_pk_fma_f32 v[4:5], v[24:25], v[34:35], v[4:5]
	v_lshlrev_b32_e32 v36, 16, v10
	v_pk_add_f32 v[4:5], v[28:29], v[4:5]
	v_and_b32_e32 v37, 0xffff0000, v10
	v_mul_f32_e32 v2, 0xbfb8aa3b, v4
	v_exp_f32_e32 v2, v2
	v_lshlrev_b32_e32 v10, 16, v11
	v_and_b32_e32 v11, 0xffff0000, v11
	v_add_f32_e32 v2, 1.0, v2
	v_rcp_f32_e32 v8, v2
	v_mul_f32_e32 v2, 0xbfb8aa3b, v5
	v_exp_f32_e32 v2, v2
	s_nop 0
	v_add_f32_e32 v2, 1.0, v2
	v_rcp_f32_e32 v9, v2
	s_nop 0
	v_pk_mul_f32 v[4:5], v[4:5], v[8:9]
	s_nop 0
	v_pk_mul_f32 v[8:9], v[4:5], v[36:37]
	v_lshlrev_b32_e32 v4, 16, v15
	v_and_b32_e32 v5, 0xffff0000, v15
	v_and_b32_e32 v15, 0xffff0000, v19
	v_pk_mul_f32 v[18:19], v[50:51], v[22:23]
	s_nop 0
	v_pk_fma_f32 v[18:19], v[52:53], v[6:7], v[18:19]
	s_nop 0
	v_pk_fma_f32 v[18:19], v[26:27], v[4:5], v[18:19]
	v_pk_mul_f32 v[4:5], v[22:23], v[4:5]
	v_pk_add_f32 v[18:19], v[30:31], v[18:19]
	v_pk_fma_f32 v[4:5], v[50:51], v[6:7], v[4:5]
	v_mul_f32_e32 v2, 0xbfb8aa3b, v18
	v_exp_f32_e32 v2, v2
	s_nop 0
	v_add_f32_e32 v2, 1.0, v2
	v_rcp_f32_e32 v20, v2
	v_mul_f32_e32 v2, 0xbfb8aa3b, v19
	v_exp_f32_e32 v2, v2
	s_nop 0
	v_add_f32_e32 v2, 1.0, v2
	v_rcp_f32_e32 v21, v2
	v_lshlrev_b32_e32 v2, 16, v3
	v_and_b32_e32 v3, 0xffff0000, v3
	v_pk_fma_f32 v[2:3], v[26:27], v[2:3], v[4:5]
	v_pk_mul_f32 v[18:19], v[18:19], v[20:21]
	v_pk_add_f32 v[2:3], v[30:31], v[2:3]
	v_pk_mul_f32 v[14:15], v[18:19], v[14:15]
	v_mul_f32_e32 v4, 0xbfb8aa3b, v2
	v_mul_f32_e32 v5, 0xbfb8aa3b, v3
	v_exp_f32_e32 v4, v4
	v_exp_f32_e32 v5, v5
	v_add_f32_e32 v4, 1.0, v4
	v_add_f32_e32 v5, 1.0, v5
	v_rcp_f32_e32 v4, v4
	v_rcp_f32_e32 v5, v5
	s_nop 0
	v_pk_mul_f32 v[2:3], v[2:3], v[4:5]
	s_nop 0
	v_pk_mul_f32 v[6:7], v[2:3], v[10:11]
	v_cvt_pk_bf16_f32 v4, v16, v17
	v_lshlrev_b32_e32 v16, 6, v68
	v_mov_b64_e32 v[10:11], s[60:61]
	v_cvt_pk_bf16_f32 v3, v12, v13
	v_cvt_pk_bf16_f32 v5, v14, v15
	v_mad_i64_i32 v[12:13], s[22:23], v16, s3, v[10:11]
	v_lshlrev_b64 v[14:15], 1, v[48:49]
	v_cvt_pk_bf16_f32 v2, v56, v57
	v_lshl_add_u64 v[12:13], v[12:13], 0, v[14:15]
	global_store_dwordx4 v[12:13], v[2:5], off
	s_nop 1
	v_cvt_pk_bf16_f32 v3, v0, v1
	v_or_b32_e32 v0, 1, v16
	v_mad_i64_i32 v[0:1], s[22:23], v0, s3, v[10:11]
	s_mov_b32 s3, 0x2bfff
	v_cmp_lt_i32_e32 vcc, s3, v66
	v_cvt_pk_bf16_f32 v2, v32, v33
	v_cvt_pk_bf16_f32 v4, v8, v9
	v_cvt_pk_bf16_f32 v5, v6, v7
	v_lshl_add_u64 v[0:1], v[0:1], 0, v[14:15]
	s_or_b64 s[24:25], vcc, s[24:25]
	global_store_dwordx4 v[0:1], v[2:5], off
	s_andn2_b64 exec, exec, s[24:25]
	s_cbranch_execz .LBB0_803
.LBB0_801:
	s_mov_b32 s3, 0x2e8ba2e9
	v_mul_hi_i32 v0, v66, s3
	s_waitcnt lgkmcnt(0)
	v_lshrrev_b32_e32 v1, 31, v0
	v_ashrrev_i32_e32 v0, 6, v0
	v_add_u32_e32 v68, v0, v1
	v_mul_i32_i24_e32 v0, 0x160, v68
	v_lshlrev_b32_e32 v0, 3, v0
	v_sub_u32_e32 v48, v67, v0
	v_mul_hi_i32_i24_e32 v1, 0x8400, v68
	v_mul_i32_i24_e32 v0, 0x8400, v68
	v_lshl_add_u64 v[0:1], s[56:57], 0, v[0:1]
	v_ashrrev_i32_e32 v49, 31, v48
	v_lshl_add_u64 v[4:5], v[48:49], 1, v[0:1]
	v_and_b32_e32 v0, 63, v68
	v_cmp_ne_u32_e32 vcc, 0, v0
	v_mov_b32_e32 v64, 0
	v_mov_b32_e32 v65, 0
	v_mov_b32_e32 v60, 0
	v_mov_b32_e32 v61, 0
	v_mov_b32_e32 v54, 0
	v_mov_b32_e32 v55, 0
	v_mov_b32_e32 v50, 0
	v_mov_b32_e32 v51, 0
	v_mov_b32_e32 v56, 0
	v_mov_b32_e32 v57, 0
	v_mov_b32_e32 v62, 0
	v_mov_b32_e32 v63, 0
	v_mov_b32_e32 v58, 0
	v_mov_b32_e32 v59, 0
	v_mov_b32_e32 v52, 0
	v_mov_b32_e32 v53, 0
	s_mov_b64 s[100:101], vcc
	s_and_saveexec_b64 s[26:27], vcc
	s_cbranch_execz .LBB0_800
	v_add_co_u32_e32 v0, vcc, 0xffff8000, v4
	s_nop 1
	v_addc_co_u32_e32 v1, vcc, -1, v5, vcc
	v_add_co_u32_e32 v6, vcc, 0xffffa000, v4
	global_load_dwordx4 v[206:209], v[0:1], off offset:-1024
	s_nop 0
	v_addc_co_u32_e32 v7, vcc, -1, v5, vcc
	global_load_dwordx4 v[210:213], v[6:7], off offset:-3584
	s_branch .LBB0_800

.LBB0_850:
	s_or_b64 exec, exec, s[6:7]
	s_and_saveexec_b64 s[6:7], s[8:9]
	s_cbranch_execz .LBB0_852
	global_atomic_add v[0:1], v190, off
.LBB0_852:
	s_or_b64 exec, exec, s[6:7]
	s_waitcnt vmcnt(0)
	buffer_inv sc1
	s_waitcnt vmcnt(0)
.LBB0_853:
	s_or_b64 exec, exec, s[4:5]
	s_waitcnt lgkmcnt(0)
	s_barrier

.LBB0_916:
	v_readlane_b32 s2, v249, 7
	v_readlane_b32 s3, v249, 8
	v_cvt_f32_u32_e32 v1, v2
	v_sub_u32_e32 v4, 0, v2
	v_rcp_iflag_f32_e32 v1, v1
	s_nop 1
	global_atomic_add v3, v153, v190, s[2:3] sc0
	v_mul_f32_e32 v1, 0x4f7ffffe, v1
	v_cvt_u32_f32_e32 v1, v1
	v_mul_lo_u32 v4, v4, v1
	v_mul_hi_u32 v4, v1, v4
	v_add_u32_e32 v1, v1, v4
	s_waitcnt vmcnt(0)
	v_mul_hi_u32 v1, v3, v1
	v_mul_lo_u32 v4, v1, v2
	v_sub_u32_e32 v4, v3, v4
	v_add_u32_e32 v5, 1, v1
	v_cmp_ge_u32_e32 vcc, v4, v2
	v_add_u32_e32 v3, 1, v3
	s_nop 0
	v_cndmask_b32_e32 v1, v1, v5, vcc
	v_sub_u32_e32 v5, v4, v2
	v_cndmask_b32_e32 v4, v4, v5, vcc
	v_add_u32_e32 v5, 1, v1
	v_cmp_ge_u32_e32 vcc, v4, v2
	s_nop 1
	v_cndmask_b32_e32 v1, v1, v5, vcc
	v_mul_lo_u32 v4, v2, v1
	v_add_u32_e32 v2, v4, v2
	v_cmp_ne_u32_e32 vcc, v3, v2
	s_and_saveexec_b64 s[2:3], vcc
	s_xor_b64 s[4:5], exec, s[2:3]
	s_cbranch_execz .LBB0_930
	s_waitcnt lgkmcnt(0)
	v_mov_b32_e32 v0, 0x3100
	global_load_dword v0, v0, s[88:89] offset:1024 sc1
	s_waitcnt vmcnt(0)
	v_cmp_eq_u32_e32 vcc, v0, v1
	s_and_saveexec_b64 s[6:7], vcc
	s_cbranch_execz .LBB0_929
	s_mov_b32 s2, 1
	s_mov_b64 s[8:9], 0
	s_branch .LBB0_920

.LBB0_922:
	v_mov_b32_e32 v0, 0x3100
	global_load_dword v0, v0, s[88:89] offset:1024 sc1
	s_add_i32 s2, s2, 1
	s_mov_b64 s[26:27], -1
	s_waitcnt vmcnt(0)
	v_cmp_ne_u32_e32 vcc, v0, v1
	s_orn2_b64 s[24:25], vcc, exec
	s_branch .LBB0_919

.LBB0_1008:
	v_mov_b32_e32 v0, 0x3100
	global_load_dword v0, v0, s[88:89] offset:1024 sc1
	s_add_i32 s2, s2, 1
	s_mov_b64 s[24:25], -1
	s_waitcnt vmcnt(0)
	v_cmp_ne_u32_e32 vcc, v0, v1
	s_orn2_b64 s[22:23], vcc, exec
	s_branch .LBB0_1005

.LBB0_1046:
	s_cmp_lt_i32 s30, s27
	s_cselect_b64 s[4:5], -1, 0
	s_cmp_gt_i32 s30, s3
	s_cselect_b64 s[6:7], -1, 0
	s_or_b64 s[4:5], s[4:5], s[6:7]
	s_and_b64 vcc, exec, s[4:5]
	s_cbranch_vccnz .LBB0_1056
	ds_read_b128 v[206:209], v235
	ds_read_b128 v[210:213], v235 offset:64
	ds_read_b128 v[214:217], v235 offset:2304
	ds_read_b128 v[218:221], v235 offset:2368
	ds_read_b128 v[222:225], v235 offset:4608
	ds_read_b128 v[226:229], v235 offset:4672
	ds_read_b128 v[230:233], v235 offset:6912
	ds_read_b128 v[240:243], v235 offset:6976
	s_add_i32 s4, s28, s30
	s_add_i32 s4, s4, 8
	s_cmp_lt_i32 s4, 6
	s_cselect_b64 s[4:5], -1, 0
	s_mov_b64 s[8:9], -1
	s_and_b64 vcc, exec, s[4:5]
	s_waitcnt lgkmcnt(7)
	v_mfma_f32_16x16x32_bf16 v[108:111], v[206:209], v[0:3], 0
	v_mfma_f32_16x16x32_bf16 v[84:87], v[206:209], v[8:11], 0
	s_waitcnt lgkmcnt(5)
	v_mfma_f32_16x16x32_bf16 v[104:107], v[214:217], v[0:3], 0
	v_mfma_f32_16x16x32_bf16 v[72:75], v[214:217], v[8:11], 0
	s_waitcnt lgkmcnt(3)
	v_mfma_f32_16x16x32_bf16 v[100:103], v[222:225], v[0:3], 0
	v_mfma_f32_16x16x32_bf16 v[68:71], v[222:225], v[8:11], 0
	s_waitcnt lgkmcnt(1)
	v_mfma_f32_16x16x32_bf16 v[96:99], v[230:233], v[0:3], 0
	v_mfma_f32_16x16x32_bf16 v[64:67], v[230:233], v[8:11], 0
	s_waitcnt lgkmcnt(0)
	v_mfma_f32_16x16x32_bf16 v[108:111], v[210:213], v[4:7], v[108:111]
	v_mfma_f32_16x16x32_bf16 v[104:107], v[218:221], v[4:7], v[104:107]
	v_mfma_f32_16x16x32_bf16 v[100:103], v[226:229], v[4:7], v[100:103]
	v_mfma_f32_16x16x32_bf16 v[96:99], v[240:243], v[4:7], v[96:99]
	v_mfma_f32_16x16x32_bf16 v[84:87], v[210:213], v[12:15], v[84:87]
	v_mfma_f32_16x16x32_bf16 v[72:75], v[218:221], v[12:15], v[72:75]
	v_mfma_f32_16x16x32_bf16 v[68:71], v[226:229], v[12:15], v[68:71]
	v_mfma_f32_16x16x32_bf16 v[64:67], v[240:243], v[12:15], v[64:67]
	s_nop 7
	s_cbranch_vccz .LBB0_1072
	s_nop 3
	v_max3_f32 v77, v108, v109, v110
	v_max3_f32 v78, v104, v105, v106
	v_max3_f32 v77, v77, v111, v107
	v_max3_f32 v77, v77, v78, s95
	v_max3_f32 v78, v100, v101, v102
	v_max3_f32 v79, v96, v97, v98
	v_max3_f32 v78, v78, v103, v99
	v_max3_f32 v77, v77, v78, v79
	v_mov_b32_e32 v78, v77
	s_nop 1
	v_permlane16_swap_b32_e32 v77, v78
	ds_read_b32 v76, v153 offset:37628
	v_max_f32_e32 v77, v77, v78
	v_mov_b32_e32 v78, v77
	s_nop 1
	v_permlane32_swap_b32_e32 v77, v78
	v_max_f32_e32 v77, v77, v78
	s_waitcnt lgkmcnt(0)
	v_fmamk_f32 v77, v77, 0x3e38aa3b, v76
	v_sub_f32_e32 v78, v77, v139
	v_cmp_ge_f32_e32 vcc, s97, v78
	v_max_f32_e32 v78, v139, v139
	v_max_f32_e32 v77, v78, v77
	s_cmp_lg_u64 vcc, exec
	v_sub_f32_e32 v78, v139, v77
	s_cselect_b64 s[6:7], -1, 0
	v_exp_f32_e32 v78, v78
	v_cndmask_b32_e64 v145, v139, v77, s[6:7]
	s_mov_b32 s100, 0x3e38aa3b
	v_sub_f32_e32 v170, v76, v145
	v_cndmask_b32_e64 v142, 1.0, v78, s[6:7]
	v_pk_fma_f32 v[76:77], v[108:109], s[100:101], v[170:171] op_sel_hi:[1,0,0]
	v_pk_fma_f32 v[78:79], v[110:111], s[100:101], v[170:171] op_sel_hi:[1,0,0]
	v_pk_fma_f32 v[80:81], v[104:105], s[100:101], v[170:171] op_sel_hi:[1,0,0]
	v_pk_fma_f32 v[82:83], v[106:107], s[100:101], v[170:171] op_sel_hi:[1,0,0]
	v_pk_fma_f32 v[88:89], v[100:101], s[100:101], v[170:171] op_sel_hi:[1,0,0]
	v_pk_fma_f32 v[90:91], v[102:103], s[100:101], v[170:171] op_sel_hi:[1,0,0]
	v_pk_fma_f32 v[92:93], v[96:97], s[100:101], v[170:171] op_sel_hi:[1,0,0]
	v_pk_fma_f32 v[94:95], v[98:99], s[100:101], v[170:171] op_sel_hi:[1,0,0]
	v_exp_f32_e32 v76, v76
	v_exp_f32_e32 v77, v77
	v_exp_f32_e32 v78, v78
	v_exp_f32_e32 v79, v79
	v_exp_f32_e32 v80, v80
	v_exp_f32_e32 v81, v81
	v_exp_f32_e32 v82, v82
	v_exp_f32_e32 v83, v83
	v_exp_f32_e32 v88, v88
	v_exp_f32_e32 v89, v89
	v_exp_f32_e32 v90, v90
	v_exp_f32_e32 v91, v91
	v_exp_f32_e32 v92, v92
	v_exp_f32_e32 v93, v93
	v_exp_f32_e32 v94, v94
	v_exp_f32_e32 v95, v95
	v_pk_add_f32 v[172:173], v[76:77], v[78:79]
	v_pk_add_f32 v[174:175], v[80:81], v[82:83]
	v_pk_add_f32 v[172:173], v[172:173], v[88:89]
	v_pk_add_f32 v[174:175], v[174:175], v[90:91]
	v_pk_add_f32 v[172:173], v[172:173], v[92:93]
	v_pk_add_f32 v[174:175], v[174:175], v[94:95]
	v_pk_add_f32 v[172:173], v[172:173], v[174:175]
	v_add_f32_e32 v147, v172, v173
	s_cbranch_execz .LBB0_1073

.LBB0_1055:
	ds_read_b64_tr_b16 v[206:207], v236 offset:18432
	ds_read_b64_tr_b16 v[208:209], v236 offset:20736
	ds_read_b64_tr_b16 v[210:211], v236 offset:18464
	ds_read_b64_tr_b16 v[212:213], v236 offset:20768
	ds_read_b64_tr_b16 v[214:215], v236 offset:18496
	ds_read_b64_tr_b16 v[216:217], v236 offset:20800
	ds_read_b64_tr_b16 v[218:219], v236 offset:18528
	ds_read_b64_tr_b16 v[220:221], v236 offset:20832
	ds_read_b64_tr_b16 v[222:223], v236 offset:23040
	ds_read_b64_tr_b16 v[224:225], v236 offset:25344
	ds_read_b64_tr_b16 v[226:227], v236 offset:23072
	ds_read_b64_tr_b16 v[228:229], v236 offset:25376
	ds_read_b64_tr_b16 v[230:231], v236 offset:23104
	ds_read_b64_tr_b16 v[232:233], v236 offset:25408
	ds_read_b64_tr_b16 v[240:241], v236 offset:23136
	ds_read_b64_tr_b16 v[242:243], v236 offset:25440
	v_cvt_pk_bf16_f32 v72, v76, v77
	v_cvt_pk_bf16_f32 v73, v78, v79
	v_cvt_pk_bf16_f32 v74, v80, v81
	v_cvt_pk_bf16_f32 v75, v82, v83
	v_cvt_pk_bf16_f32 v76, v96, v97
	v_cvt_pk_bf16_f32 v77, v98, v99
	v_cvt_pk_bf16_f32 v78, v100, v101
	v_cvt_pk_bf16_f32 v79, v102, v103
	v_cvt_pk_bf16_f32 v68, v88, v89
	v_cvt_pk_bf16_f32 v69, v90, v91
	v_cvt_pk_bf16_f32 v70, v92, v93
	v_cvt_pk_bf16_f32 v71, v94, v95
	v_cvt_pk_bf16_f32 v64, v104, v105
	v_cvt_pk_bf16_f32 v65, v106, v107
	v_cvt_pk_bf16_f32 v66, v108, v109
	v_cvt_pk_bf16_f32 v67, v110, v111
	v_add_f32_e32 v135, v147, v135
	v_add_f32_e32 v131, v139, v131
	s_waitcnt lgkmcnt(8)
	v_mfma_f32_16x16x32_bf16 v[56:59], v[206:209], v[72:75], v[56:59]
	v_mfma_f32_16x16x32_bf16 v[40:43], v[206:209], v[76:79], v[40:43]
	v_mfma_f32_16x16x32_bf16 v[60:63], v[210:213], v[72:75], v[60:63]
	v_mfma_f32_16x16x32_bf16 v[48:51], v[210:213], v[76:79], v[48:51]
	v_mfma_f32_16x16x32_bf16 v[52:55], v[214:217], v[72:75], v[52:55]
	v_mfma_f32_16x16x32_bf16 v[36:39], v[214:217], v[76:79], v[36:39]
	v_mfma_f32_16x16x32_bf16 v[44:47], v[218:221], v[72:75], v[44:47]
	v_mfma_f32_16x16x32_bf16 v[32:35], v[218:221], v[76:79], v[32:35]
	s_waitcnt lgkmcnt(0)
	v_mfma_f32_16x16x32_bf16 v[56:59], v[222:225], v[68:71], v[56:59]
	v_mfma_f32_16x16x32_bf16 v[40:43], v[222:225], v[64:67], v[40:43]
	v_mfma_f32_16x16x32_bf16 v[60:63], v[226:229], v[68:71], v[60:63]
	v_mfma_f32_16x16x32_bf16 v[48:51], v[226:229], v[64:67], v[48:51]
	v_mfma_f32_16x16x32_bf16 v[52:55], v[230:233], v[68:71], v[52:55]
	v_mfma_f32_16x16x32_bf16 v[36:39], v[230:233], v[64:67], v[36:39]
	v_mfma_f32_16x16x32_bf16 v[44:47], v[240:243], v[68:71], v[44:47]
	v_mfma_f32_16x16x32_bf16 v[32:35], v[240:243], v[64:67], v[32:35]
	s_add_i32 s4, s30, 1
	s_cmp_ge_i32 s4, s2
	s_cbranch_scc0 .LBB0_1057
	s_branch .LBB0_1069

.LBB0_1059:
	s_cmp_lt_i32 s4, s27
	s_cselect_b64 s[4:5], -1, 0
	s_cmp_ge_i32 s30, s3
	s_cselect_b64 s[6:7], -1, 0
	s_or_b64 s[4:5], s[6:7], s[4:5]
	s_and_b64 vcc, exec, s[4:5]
	s_cbranch_vccnz .LBB0_1069
	ds_read_b128 v[206:209], v235 offset:9216
	ds_read_b128 v[210:213], v235 offset:9280
	ds_read_b128 v[214:217], v235 offset:11520
	ds_read_b128 v[218:221], v235 offset:11584
	ds_read_b128 v[222:225], v235 offset:13824
	ds_read_b128 v[226:229], v235 offset:13888
	ds_read_b128 v[230:233], v235 offset:16128
	ds_read_b128 v[240:243], v235 offset:16192
	s_add_i32 s4, s28, s30
	s_add_i32 s4, s4, 9
	s_cmp_lt_i32 s4, 6
	s_cselect_b64 s[4:5], -1, 0
	s_mov_b64 s[8:9], -1
	s_and_b64 vcc, exec, s[4:5]
	s_waitcnt lgkmcnt(7)
	v_mfma_f32_16x16x32_bf16 v[108:111], v[206:209], v[0:3], 0
	v_mfma_f32_16x16x32_bf16 v[84:87], v[206:209], v[8:11], 0
	s_waitcnt lgkmcnt(5)
	v_mfma_f32_16x16x32_bf16 v[104:107], v[214:217], v[0:3], 0
	v_mfma_f32_16x16x32_bf16 v[72:75], v[214:217], v[8:11], 0
	s_waitcnt lgkmcnt(3)
	v_mfma_f32_16x16x32_bf16 v[100:103], v[222:225], v[0:3], 0
	v_mfma_f32_16x16x32_bf16 v[68:71], v[222:225], v[8:11], 0
	s_waitcnt lgkmcnt(1)
	v_mfma_f32_16x16x32_bf16 v[96:99], v[230:233], v[0:3], 0
	v_mfma_f32_16x16x32_bf16 v[64:67], v[230:233], v[8:11], 0
	s_waitcnt lgkmcnt(0)
	v_mfma_f32_16x16x32_bf16 v[108:111], v[210:213], v[4:7], v[108:111]
	v_mfma_f32_16x16x32_bf16 v[104:107], v[218:221], v[4:7], v[104:107]
	v_mfma_f32_16x16x32_bf16 v[100:103], v[226:229], v[4:7], v[100:103]
	v_mfma_f32_16x16x32_bf16 v[96:99], v[240:243], v[4:7], v[96:99]
	v_mfma_f32_16x16x32_bf16 v[84:87], v[210:213], v[12:15], v[84:87]
	v_mfma_f32_16x16x32_bf16 v[72:75], v[218:221], v[12:15], v[72:75]
	v_mfma_f32_16x16x32_bf16 v[68:71], v[226:229], v[12:15], v[68:71]
	v_mfma_f32_16x16x32_bf16 v[64:67], v[240:243], v[12:15], v[64:67]
	s_nop 7
	s_cbranch_vccz .LBB0_1076
	s_nop 3
	v_max3_f32 v77, v108, v109, v110
	v_max3_f32 v78, v104, v105, v106
	v_max3_f32 v77, v77, v111, v107
	v_max3_f32 v77, v77, v78, s95
	v_max3_f32 v78, v100, v101, v102
	v_max3_f32 v79, v96, v97, v98
	v_max3_f32 v78, v78, v103, v99
	v_max3_f32 v77, v77, v78, v79
	v_mov_b32_e32 v78, v77
	s_nop 1
	v_permlane16_swap_b32_e32 v77, v78
	ds_read_b32 v76, v153 offset:37628
	v_max_f32_e32 v77, v77, v78
	v_mov_b32_e32 v78, v77
	s_nop 1
	v_permlane32_swap_b32_e32 v77, v78
	v_max_f32_e32 v77, v77, v78
	s_waitcnt lgkmcnt(0)
	v_fmamk_f32 v77, v77, 0x3e38aa3b, v76
	v_sub_f32_e32 v78, v77, v145
	v_cmp_ge_f32_e32 vcc, s97, v78
	v_max_f32_e32 v78, v145, v145
	v_max_f32_e32 v77, v78, v77
	s_cmp_lg_u64 vcc, exec
	v_sub_f32_e32 v78, v145, v77
	s_cselect_b64 s[6:7], -1, 0
	v_exp_f32_e32 v78, v78
	v_cndmask_b32_e64 v139, v145, v77, s[6:7]
	s_mov_b32 s100, 0x3e38aa3b
	v_sub_f32_e32 v170, v76, v139
	v_cndmask_b32_e64 v142, 1.0, v78, s[6:7]
	v_pk_fma_f32 v[76:77], v[108:109], s[100:101], v[170:171] op_sel_hi:[1,0,0]
	v_pk_fma_f32 v[78:79], v[110:111], s[100:101], v[170:171] op_sel_hi:[1,0,0]
	v_pk_fma_f32 v[80:81], v[104:105], s[100:101], v[170:171] op_sel_hi:[1,0,0]
	v_pk_fma_f32 v[82:83], v[106:107], s[100:101], v[170:171] op_sel_hi:[1,0,0]
	v_pk_fma_f32 v[88:89], v[100:101], s[100:101], v[170:171] op_sel_hi:[1,0,0]
	v_pk_fma_f32 v[90:91], v[102:103], s[100:101], v[170:171] op_sel_hi:[1,0,0]
	v_pk_fma_f32 v[92:93], v[96:97], s[100:101], v[170:171] op_sel_hi:[1,0,0]
	v_pk_fma_f32 v[94:95], v[98:99], s[100:101], v[170:171] op_sel_hi:[1,0,0]
	v_exp_f32_e32 v76, v76
	v_exp_f32_e32 v77, v77
	v_exp_f32_e32 v78, v78
	v_exp_f32_e32 v79, v79
	v_exp_f32_e32 v80, v80
	v_exp_f32_e32 v81, v81
	v_exp_f32_e32 v82, v82
	v_exp_f32_e32 v83, v83
	v_exp_f32_e32 v88, v88
	v_exp_f32_e32 v89, v89
	v_exp_f32_e32 v90, v90
	v_exp_f32_e32 v91, v91
	v_exp_f32_e32 v92, v92
	v_exp_f32_e32 v93, v93
	v_exp_f32_e32 v94, v94
	v_exp_f32_e32 v95, v95
	v_pk_add_f32 v[172:173], v[76:77], v[78:79]
	v_pk_add_f32 v[174:175], v[80:81], v[82:83]
	v_pk_add_f32 v[172:173], v[172:173], v[88:89]
	v_pk_add_f32 v[174:175], v[174:175], v[90:91]
	v_pk_add_f32 v[172:173], v[172:173], v[92:93]
	v_pk_add_f32 v[174:175], v[174:175], v[94:95]
	v_pk_add_f32 v[172:173], v[172:173], v[174:175]
	v_add_f32_e32 v147, v172, v173
	s_cbranch_execz .LBB0_1077

.LBB0_1068:
	ds_read_b64_tr_b16 v[206:207], v236 offset:27648
	ds_read_b64_tr_b16 v[208:209], v236 offset:29952
	ds_read_b64_tr_b16 v[210:211], v236 offset:27680
	ds_read_b64_tr_b16 v[212:213], v236 offset:29984
	ds_read_b64_tr_b16 v[214:215], v236 offset:27712
	ds_read_b64_tr_b16 v[216:217], v236 offset:30016
	ds_read_b64_tr_b16 v[218:219], v236 offset:27744
	ds_read_b64_tr_b16 v[220:221], v236 offset:30048
	ds_read_b64_tr_b16 v[222:223], v236 offset:32256
	ds_read_b64_tr_b16 v[224:225], v236 offset:34560
	ds_read_b64_tr_b16 v[226:227], v236 offset:32288
	ds_read_b64_tr_b16 v[228:229], v236 offset:34592
	ds_read_b64_tr_b16 v[230:231], v236 offset:32320
	ds_read_b64_tr_b16 v[232:233], v236 offset:34624
	ds_read_b64_tr_b16 v[240:241], v236 offset:32352
	ds_read_b64_tr_b16 v[242:243], v236 offset:34656
	v_cvt_pk_bf16_f32 v72, v76, v77
	v_cvt_pk_bf16_f32 v73, v78, v79
	v_cvt_pk_bf16_f32 v74, v80, v81
	v_cvt_pk_bf16_f32 v75, v82, v83
	v_cvt_pk_bf16_f32 v76, v96, v97
	v_cvt_pk_bf16_f32 v77, v98, v99
	v_cvt_pk_bf16_f32 v78, v100, v101
	v_cvt_pk_bf16_f32 v79, v102, v103
	v_cvt_pk_bf16_f32 v68, v88, v89
	v_cvt_pk_bf16_f32 v69, v90, v91
	v_cvt_pk_bf16_f32 v70, v92, v93
	v_cvt_pk_bf16_f32 v71, v94, v95
	v_cvt_pk_bf16_f32 v64, v104, v105
	v_cvt_pk_bf16_f32 v65, v106, v107
	v_cvt_pk_bf16_f32 v66, v108, v109
	v_cvt_pk_bf16_f32 v67, v110, v111
	v_add_f32_e32 v135, v147, v135
	v_add_f32_e32 v131, v145, v131
	s_waitcnt lgkmcnt(8)
	v_mfma_f32_16x16x32_bf16 v[56:59], v[206:209], v[72:75], v[56:59]
	v_mfma_f32_16x16x32_bf16 v[40:43], v[206:209], v[76:79], v[40:43]
	v_mfma_f32_16x16x32_bf16 v[60:63], v[210:213], v[72:75], v[60:63]
	v_mfma_f32_16x16x32_bf16 v[48:51], v[210:213], v[76:79], v[48:51]
	v_mfma_f32_16x16x32_bf16 v[52:55], v[214:217], v[72:75], v[52:55]
	v_mfma_f32_16x16x32_bf16 v[36:39], v[214:217], v[76:79], v[36:39]
	v_mfma_f32_16x16x32_bf16 v[44:47], v[218:221], v[72:75], v[44:47]
	v_mfma_f32_16x16x32_bf16 v[32:35], v[218:221], v[76:79], v[32:35]
	s_waitcnt lgkmcnt(0)
	v_mfma_f32_16x16x32_bf16 v[56:59], v[222:225], v[68:71], v[56:59]
	v_mfma_f32_16x16x32_bf16 v[40:43], v[222:225], v[64:67], v[40:43]
	v_mfma_f32_16x16x32_bf16 v[60:63], v[226:229], v[68:71], v[60:63]
	v_mfma_f32_16x16x32_bf16 v[48:51], v[226:229], v[64:67], v[48:51]
	v_mfma_f32_16x16x32_bf16 v[52:55], v[230:233], v[68:71], v[52:55]
	v_mfma_f32_16x16x32_bf16 v[36:39], v[230:233], v[64:67], v[36:39]
	v_mfma_f32_16x16x32_bf16 v[44:47], v[240:243], v[68:71], v[44:47]
	v_mfma_f32_16x16x32_bf16 v[32:35], v[240:243], v[64:67], v[32:35]
	s_branch .LBB0_1070
